# W_bc weight fold moved to the f32 matrix cores (v_mfma_f32_16x16x4_f32, f32 operands/accumulate), one 16x64 tile per wave after the streaming jobs
# speedup vs baseline: 1.0227x; 1.0123x over previous
.LBB0_9:
	v_cmp_gt_u32_e32 vcc, 0x100, v157
	s_cmp_eq_u32 s3, 1
	s_cselect_b64 s[64:65], -1, 0
	s_nop 0
	s_and_b64 vcc, vcc, s[64:65]
	s_and_saveexec_b64 s[62:63], vcc
	s_cbranch_execz .LBB0_15
	s_load_dwordx2 s[12:13], s[44:45], 0x68
	s_load_dwordx4 s[28:31], s[44:45], 0x58
	v_lshrrev_b32_e32 v2, 6, v157
	v_and_b32_e32 v68, 15, v157
	v_bfe_u32 v69, v157, 4, 2
	s_lshl_b32 s65, s2, 2
	v_readfirstlane_b32 s64, v2
	v_lshlrev_b32_e32 v128, 10, v68
	v_lshlrev_b32_e32 v129, 4, v69
	v_lshlrev_b32_e32 v133, 14, v69
	v_lshlrev_b32_e32 v131, 13, v68
	s_add_i32 s64, s64, s65
	s_lshl_b32 s65, s42, 2
	v_lshl_add_u32 v128, v69, 4, v128
	v_lshl_add_u32 v133, v68, 4, v133
	v_lshl_add_u32 v131, v69, 3, v131
	s_nop 0
	v_add_u32_e32 v132, 0x1000, v131
	s_waitcnt lgkmcnt(0)
.Lwb_tile:
	s_cmp_lt_u32 s64, 0x400
	s_cbranch_scc0 .LBB0_15
	s_lshr_b32 s3, s64, 8
	s_bfe_u32 s35, s64, 0x40004
	s_lshl_b32 s66, s3, 18
	s_lshl_b32 s67, s35, 14
	s_add_u32 s66, s66, s67
	s_add_u32 s66, s28, s66
	s_addc_u32 s67, s29, 0
	s_lshl_b32 s68, s3, 10
	s_add_u32 s68, s30, s68
	s_addc_u32 s69, s31, 0
	s_and_b32 s70, s64, 15
	s_lshl_b32 s71, s70, 8
	s_lshl_b32 s92, s3, 20
	s_add_u32 s71, s71, s92
	s_add_u32 s71, s71, 0x1000
	s_add_u32 s92, s12, s71
	s_addc_u32 s93, s13, 0
	s_lshl_b32 s94, s70, 17
	s_lshr_b32 s95, s64, 4
	s_lshl_b32 s95, s95, 5
	s_add_u32 s94, s94, s95
	s_add_u32 s94, s48, s94
	s_addc_u32 s95, s49, 0
	v_mov_b32_e32 v130, v133
	v_add_u32_e32 v2, 0x2000, v133
	v_mov_b32_e32 v4, 0
	v_mov_b32_e32 v5, 0
	v_mov_b32_e32 v6, 0
	v_mov_b32_e32 v7, 0
	v_mov_b32_e32 v8, 0
	v_mov_b32_e32 v9, 0
	v_mov_b32_e32 v10, 0
	v_mov_b32_e32 v11, 0
	v_mov_b32_e32 v12, 0
	v_mov_b32_e32 v13, 0
	v_mov_b32_e32 v14, 0
	v_mov_b32_e32 v15, 0
	v_mov_b32_e32 v16, 0
	v_mov_b32_e32 v17, 0
	v_mov_b32_e32 v18, 0
	v_mov_b32_e32 v19, 0
	global_load_dwordx4 v[20:23], v128, s[66:67]
	global_load_dwordx4 v[24:27], v129, s[68:69]
	global_load_dwordx4 v[28:31], v130, s[92:93] offset:-4096
	global_load_dwordx4 v[32:35], v130, s[92:93]
	global_load_dwordx4 v[36:39], v2, s[92:93] offset:-4096
	global_load_dwordx4 v[40:43], v2, s[92:93]
	s_nop 0
	v_add_u32_e32 v130, 0x10000, v130
	v_add_u32_e32 v2, 0x10000, v2
	s_nop 0
	global_load_dwordx4 v[44:47], v128, s[66:67] offset:64
	global_load_dwordx4 v[48:51], v129, s[68:69] offset:64
	global_load_dwordx4 v[52:55], v130, s[92:93] offset:-4096
	global_load_dwordx4 v[56:59], v130, s[92:93]
	global_load_dwordx4 v[60:63], v2, s[92:93] offset:-4096
	global_load_dwordx4 v[64:67], v2, s[92:93]
	v_add_u32_e32 v130, 0x10000, v130
	v_add_u32_e32 v2, 0x10000, v2
	s_nop 0
	global_load_dwordx4 v[92:95], v128, s[66:67] offset:128
	global_load_dwordx4 v[96:99], v129, s[68:69] offset:128
	global_load_dwordx4 v[112:115], v130, s[92:93] offset:-4096
	global_load_dwordx4 v[116:119], v130, s[92:93]
	global_load_dwordx4 v[120:123], v2, s[92:93] offset:-4096
	global_load_dwordx4 v[124:127], v2, s[92:93]
	s_waitcnt vmcnt(12)
	v_pk_mul_f32 v[20:21], v[20:21], v[24:25]
	v_pk_mul_f32 v[22:23], v[22:23], v[26:27]
	s_nop 1
	v_mfma_f32_16x16x4_f32 v[4:7], v20, v28, v[4:7]
	v_mfma_f32_16x16x4_f32 v[8:11], v20, v29, v[8:11]
	v_mfma_f32_16x16x4_f32 v[12:15], v20, v30, v[12:15]
	v_mfma_f32_16x16x4_f32 v[16:19], v20, v31, v[16:19]
	v_mfma_f32_16x16x4_f32 v[4:7], v21, v32, v[4:7]
	v_mfma_f32_16x16x4_f32 v[8:11], v21, v33, v[8:11]
	v_mfma_f32_16x16x4_f32 v[12:15], v21, v34, v[12:15]
	v_mfma_f32_16x16x4_f32 v[16:19], v21, v35, v[16:19]
	v_mfma_f32_16x16x4_f32 v[4:7], v22, v36, v[4:7]
	v_mfma_f32_16x16x4_f32 v[8:11], v22, v37, v[8:11]
	v_mfma_f32_16x16x4_f32 v[12:15], v22, v38, v[12:15]
	v_mfma_f32_16x16x4_f32 v[16:19], v22, v39, v[16:19]
	v_mfma_f32_16x16x4_f32 v[4:7], v23, v40, v[4:7]
	v_mfma_f32_16x16x4_f32 v[8:11], v23, v41, v[8:11]
	v_mfma_f32_16x16x4_f32 v[12:15], v23, v42, v[12:15]
	v_mfma_f32_16x16x4_f32 v[16:19], v23, v43, v[16:19]
	v_add_u32_e32 v130, 0x10000, v130
	v_add_u32_e32 v2, 0x10000, v2
	s_nop 0
	global_load_dwordx4 v[20:23], v128, s[66:67] offset:192
	global_load_dwordx4 v[24:27], v129, s[68:69] offset:192
	global_load_dwordx4 v[28:31], v130, s[92:93] offset:-4096
	global_load_dwordx4 v[32:35], v130, s[92:93]
	global_load_dwordx4 v[36:39], v2, s[92:93] offset:-4096
	global_load_dwordx4 v[40:43], v2, s[92:93]
	s_waitcnt vmcnt(12)
	v_pk_mul_f32 v[44:45], v[44:45], v[48:49]
	v_pk_mul_f32 v[46:47], v[46:47], v[50:51]
	s_nop 1
	v_mfma_f32_16x16x4_f32 v[4:7], v44, v52, v[4:7]
	v_mfma_f32_16x16x4_f32 v[8:11], v44, v53, v[8:11]
	v_mfma_f32_16x16x4_f32 v[12:15], v44, v54, v[12:15]
	v_mfma_f32_16x16x4_f32 v[16:19], v44, v55, v[16:19]
	v_mfma_f32_16x16x4_f32 v[4:7], v45, v56, v[4:7]
	v_mfma_f32_16x16x4_f32 v[8:11], v45, v57, v[8:11]
	v_mfma_f32_16x16x4_f32 v[12:15], v45, v58, v[12:15]
	v_mfma_f32_16x16x4_f32 v[16:19], v45, v59, v[16:19]
	v_mfma_f32_16x16x4_f32 v[4:7], v46, v60, v[4:7]
	v_mfma_f32_16x16x4_f32 v[8:11], v46, v61, v[8:11]
	v_mfma_f32_16x16x4_f32 v[12:15], v46, v62, v[12:15]
	v_mfma_f32_16x16x4_f32 v[16:19], v46, v63, v[16:19]
	v_mfma_f32_16x16x4_f32 v[4:7], v47, v64, v[4:7]
	v_mfma_f32_16x16x4_f32 v[8:11], v47, v65, v[8:11]
	v_mfma_f32_16x16x4_f32 v[12:15], v47, v66, v[12:15]
	v_mfma_f32_16x16x4_f32 v[16:19], v47, v67, v[16:19]
	v_add_u32_e32 v130, 0x10000, v130
	v_add_u32_e32 v2, 0x10000, v2
	s_nop 0
	global_load_dwordx4 v[44:47], v128, s[66:67] offset:256
	global_load_dwordx4 v[48:51], v129, s[68:69] offset:256
	global_load_dwordx4 v[52:55], v130, s[92:93] offset:-4096
	global_load_dwordx4 v[56:59], v130, s[92:93]
	global_load_dwordx4 v[60:63], v2, s[92:93] offset:-4096
	global_load_dwordx4 v[64:67], v2, s[92:93]
	s_waitcnt vmcnt(12)
	v_pk_mul_f32 v[92:93], v[92:93], v[96:97]
	v_pk_mul_f32 v[94:95], v[94:95], v[98:99]
	s_nop 1
	v_mfma_f32_16x16x4_f32 v[4:7], v92, v112, v[4:7]
	v_mfma_f32_16x16x4_f32 v[8:11], v92, v113, v[8:11]
	v_mfma_f32_16x16x4_f32 v[12:15], v92, v114, v[12:15]
	v_mfma_f32_16x16x4_f32 v[16:19], v92, v115, v[16:19]
	v_mfma_f32_16x16x4_f32 v[4:7], v93, v116, v[4:7]
	v_mfma_f32_16x16x4_f32 v[8:11], v93, v117, v[8:11]
	v_mfma_f32_16x16x4_f32 v[12:15], v93, v118, v[12:15]
	v_mfma_f32_16x16x4_f32 v[16:19], v93, v119, v[16:19]
	v_mfma_f32_16x16x4_f32 v[4:7], v94, v120, v[4:7]
	v_mfma_f32_16x16x4_f32 v[8:11], v94, v121, v[8:11]
	v_mfma_f32_16x16x4_f32 v[12:15], v94, v122, v[12:15]
	v_mfma_f32_16x16x4_f32 v[16:19], v94, v123, v[16:19]
	v_mfma_f32_16x16x4_f32 v[4:7], v95, v124, v[4:7]
	v_mfma_f32_16x16x4_f32 v[8:11], v95, v125, v[8:11]
	v_mfma_f32_16x16x4_f32 v[12:15], v95, v126, v[12:15]
	v_mfma_f32_16x16x4_f32 v[16:19], v95, v127, v[16:19]
	v_add_u32_e32 v130, 0x10000, v130
	v_add_u32_e32 v2, 0x10000, v2
	s_nop 0
	global_load_dwordx4 v[92:95], v128, s[66:67] offset:320
	global_load_dwordx4 v[96:99], v129, s[68:69] offset:320
	global_load_dwordx4 v[112:115], v130, s[92:93] offset:-4096
	global_load_dwordx4 v[116:119], v130, s[92:93]
	global_load_dwordx4 v[120:123], v2, s[92:93] offset:-4096
	global_load_dwordx4 v[124:127], v2, s[92:93]
	s_waitcnt vmcnt(12)
	v_pk_mul_f32 v[20:21], v[20:21], v[24:25]
	v_pk_mul_f32 v[22:23], v[22:23], v[26:27]
	s_nop 1
	v_mfma_f32_16x16x4_f32 v[4:7], v20, v28, v[4:7]
	v_mfma_f32_16x16x4_f32 v[8:11], v20, v29, v[8:11]
	v_mfma_f32_16x16x4_f32 v[12:15], v20, v30, v[12:15]
	v_mfma_f32_16x16x4_f32 v[16:19], v20, v31, v[16:19]
	v_mfma_f32_16x16x4_f32 v[4:7], v21, v32, v[4:7]
	v_mfma_f32_16x16x4_f32 v[8:11], v21, v33, v[8:11]
	v_mfma_f32_16x16x4_f32 v[12:15], v21, v34, v[12:15]
	v_mfma_f32_16x16x4_f32 v[16:19], v21, v35, v[16:19]
	v_mfma_f32_16x16x4_f32 v[4:7], v22, v36, v[4:7]
	v_mfma_f32_16x16x4_f32 v[8:11], v22, v37, v[8:11]
	v_mfma_f32_16x16x4_f32 v[12:15], v22, v38, v[12:15]
	v_mfma_f32_16x16x4_f32 v[16:19], v22, v39, v[16:19]
	v_mfma_f32_16x16x4_f32 v[4:7], v23, v40, v[4:7]
	v_mfma_f32_16x16x4_f32 v[8:11], v23, v41, v[8:11]
	v_mfma_f32_16x16x4_f32 v[12:15], v23, v42, v[12:15]
	v_mfma_f32_16x16x4_f32 v[16:19], v23, v43, v[16:19]
	v_add_u32_e32 v130, 0x10000, v130
	v_add_u32_e32 v2, 0x10000, v2
	s_nop 0
	global_load_dwordx4 v[20:23], v128, s[66:67] offset:384
	global_load_dwordx4 v[24:27], v129, s[68:69] offset:384
	global_load_dwordx4 v[28:31], v130, s[92:93] offset:-4096
	global_load_dwordx4 v[32:35], v130, s[92:93]
	global_load_dwordx4 v[36:39], v2, s[92:93] offset:-4096
	global_load_dwordx4 v[40:43], v2, s[92:93]
	s_waitcnt vmcnt(12)
	v_pk_mul_f32 v[44:45], v[44:45], v[48:49]
	v_pk_mul_f32 v[46:47], v[46:47], v[50:51]
	s_nop 1
	v_mfma_f32_16x16x4_f32 v[4:7], v44, v52, v[4:7]
	v_mfma_f32_16x16x4_f32 v[8:11], v44, v53, v[8:11]
	v_mfma_f32_16x16x4_f32 v[12:15], v44, v54, v[12:15]
	v_mfma_f32_16x16x4_f32 v[16:19], v44, v55, v[16:19]
	v_mfma_f32_16x16x4_f32 v[4:7], v45, v56, v[4:7]
	v_mfma_f32_16x16x4_f32 v[8:11], v45, v57, v[8:11]
	v_mfma_f32_16x16x4_f32 v[12:15], v45, v58, v[12:15]
	v_mfma_f32_16x16x4_f32 v[16:19], v45, v59, v[16:19]
	v_mfma_f32_16x16x4_f32 v[4:7], v46, v60, v[4:7]
	v_mfma_f32_16x16x4_f32 v[8:11], v46, v61, v[8:11]
	v_mfma_f32_16x16x4_f32 v[12:15], v46, v62, v[12:15]
	v_mfma_f32_16x16x4_f32 v[16:19], v46, v63, v[16:19]
	v_mfma_f32_16x16x4_f32 v[4:7], v47, v64, v[4:7]
	v_mfma_f32_16x16x4_f32 v[8:11], v47, v65, v[8:11]
	v_mfma_f32_16x16x4_f32 v[12:15], v47, v66, v[12:15]
	v_mfma_f32_16x16x4_f32 v[16:19], v47, v67, v[16:19]
	v_add_u32_e32 v130, 0x10000, v130
	v_add_u32_e32 v2, 0x10000, v2
	s_nop 0
	global_load_dwordx4 v[44:47], v128, s[66:67] offset:448
	global_load_dwordx4 v[48:51], v129, s[68:69] offset:448
	global_load_dwordx4 v[52:55], v130, s[92:93] offset:-4096
	global_load_dwordx4 v[56:59], v130, s[92:93]
	global_load_dwordx4 v[60:63], v2, s[92:93] offset:-4096
	global_load_dwordx4 v[64:67], v2, s[92:93]
	s_waitcnt vmcnt(12)
	v_pk_mul_f32 v[92:93], v[92:93], v[96:97]
	v_pk_mul_f32 v[94:95], v[94:95], v[98:99]
	s_nop 1
	v_mfma_f32_16x16x4_f32 v[4:7], v92, v112, v[4:7]
	v_mfma_f32_16x16x4_f32 v[8:11], v92, v113, v[8:11]
	v_mfma_f32_16x16x4_f32 v[12:15], v92, v114, v[12:15]
	v_mfma_f32_16x16x4_f32 v[16:19], v92, v115, v[16:19]
	v_mfma_f32_16x16x4_f32 v[4:7], v93, v116, v[4:7]
	v_mfma_f32_16x16x4_f32 v[8:11], v93, v117, v[8:11]
	v_mfma_f32_16x16x4_f32 v[12:15], v93, v118, v[12:15]
	v_mfma_f32_16x16x4_f32 v[16:19], v93, v119, v[16:19]
	v_mfma_f32_16x16x4_f32 v[4:7], v94, v120, v[4:7]
	v_mfma_f32_16x16x4_f32 v[8:11], v94, v121, v[8:11]
	v_mfma_f32_16x16x4_f32 v[12:15], v94, v122, v[12:15]
	v_mfma_f32_16x16x4_f32 v[16:19], v94, v123, v[16:19]
	v_mfma_f32_16x16x4_f32 v[4:7], v95, v124, v[4:7]
	v_mfma_f32_16x16x4_f32 v[8:11], v95, v125, v[8:11]
	v_mfma_f32_16x16x4_f32 v[12:15], v95, v126, v[12:15]
	v_mfma_f32_16x16x4_f32 v[16:19], v95, v127, v[16:19]
	v_add_u32_e32 v130, 0x10000, v130
	v_add_u32_e32 v2, 0x10000, v2
	s_nop 0
	global_load_dwordx4 v[92:95], v128, s[66:67] offset:512
	global_load_dwordx4 v[96:99], v129, s[68:69] offset:512
	global_load_dwordx4 v[112:115], v130, s[92:93] offset:-4096
	global_load_dwordx4 v[116:119], v130, s[92:93]
	global_load_dwordx4 v[120:123], v2, s[92:93] offset:-4096
	global_load_dwordx4 v[124:127], v2, s[92:93]
	s_waitcnt vmcnt(12)
	v_pk_mul_f32 v[20:21], v[20:21], v[24:25]
	v_pk_mul_f32 v[22:23], v[22:23], v[26:27]
	s_nop 1
	v_mfma_f32_16x16x4_f32 v[4:7], v20, v28, v[4:7]
	v_mfma_f32_16x16x4_f32 v[8:11], v20, v29, v[8:11]
	v_mfma_f32_16x16x4_f32 v[12:15], v20, v30, v[12:15]
	v_mfma_f32_16x16x4_f32 v[16:19], v20, v31, v[16:19]
	v_mfma_f32_16x16x4_f32 v[4:7], v21, v32, v[4:7]
	v_mfma_f32_16x16x4_f32 v[8:11], v21, v33, v[8:11]
	v_mfma_f32_16x16x4_f32 v[12:15], v21, v34, v[12:15]
	v_mfma_f32_16x16x4_f32 v[16:19], v21, v35, v[16:19]
	v_mfma_f32_16x16x4_f32 v[4:7], v22, v36, v[4:7]
	v_mfma_f32_16x16x4_f32 v[8:11], v22, v37, v[8:11]
	v_mfma_f32_16x16x4_f32 v[12:15], v22, v38, v[12:15]
	v_mfma_f32_16x16x4_f32 v[16:19], v22, v39, v[16:19]
	v_mfma_f32_16x16x4_f32 v[4:7], v23, v40, v[4:7]
	v_mfma_f32_16x16x4_f32 v[8:11], v23, v41, v[8:11]
	v_mfma_f32_16x16x4_f32 v[12:15], v23, v42, v[12:15]
	v_mfma_f32_16x16x4_f32 v[16:19], v23, v43, v[16:19]
	v_add_u32_e32 v130, 0x10000, v130
	v_add_u32_e32 v2, 0x10000, v2
	s_nop 0
	global_load_dwordx4 v[20:23], v128, s[66:67] offset:576
	global_load_dwordx4 v[24:27], v129, s[68:69] offset:576
	global_load_dwordx4 v[28:31], v130, s[92:93] offset:-4096
	global_load_dwordx4 v[32:35], v130, s[92:93]
	global_load_dwordx4 v[36:39], v2, s[92:93] offset:-4096
	global_load_dwordx4 v[40:43], v2, s[92:93]
	s_waitcnt vmcnt(12)
	v_pk_mul_f32 v[44:45], v[44:45], v[48:49]
	v_pk_mul_f32 v[46:47], v[46:47], v[50:51]
	s_nop 1
	v_mfma_f32_16x16x4_f32 v[4:7], v44, v52, v[4:7]
	v_mfma_f32_16x16x4_f32 v[8:11], v44, v53, v[8:11]
	v_mfma_f32_16x16x4_f32 v[12:15], v44, v54, v[12:15]
	v_mfma_f32_16x16x4_f32 v[16:19], v44, v55, v[16:19]
	v_mfma_f32_16x16x4_f32 v[4:7], v45, v56, v[4:7]
	v_mfma_f32_16x16x4_f32 v[8:11], v45, v57, v[8:11]
	v_mfma_f32_16x16x4_f32 v[12:15], v45, v58, v[12:15]
	v_mfma_f32_16x16x4_f32 v[16:19], v45, v59, v[16:19]
	v_mfma_f32_16x16x4_f32 v[4:7], v46, v60, v[4:7]
	v_mfma_f32_16x16x4_f32 v[8:11], v46, v61, v[8:11]
	v_mfma_f32_16x16x4_f32 v[12:15], v46, v62, v[12:15]
	v_mfma_f32_16x16x4_f32 v[16:19], v46, v63, v[16:19]
	v_mfma_f32_16x16x4_f32 v[4:7], v47, v64, v[4:7]
	v_mfma_f32_16x16x4_f32 v[8:11], v47, v65, v[8:11]
	v_mfma_f32_16x16x4_f32 v[12:15], v47, v66, v[12:15]
	v_mfma_f32_16x16x4_f32 v[16:19], v47, v67, v[16:19]
	v_add_u32_e32 v130, 0x10000, v130
	v_add_u32_e32 v2, 0x10000, v2
	s_nop 0
	global_load_dwordx4 v[44:47], v128, s[66:67] offset:640
	global_load_dwordx4 v[48:51], v129, s[68:69] offset:640
	global_load_dwordx4 v[52:55], v130, s[92:93] offset:-4096
	global_load_dwordx4 v[56:59], v130, s[92:93]
	global_load_dwordx4 v[60:63], v2, s[92:93] offset:-4096
	global_load_dwordx4 v[64:67], v2, s[92:93]
	s_waitcnt vmcnt(12)
	v_pk_mul_f32 v[92:93], v[92:93], v[96:97]
	v_pk_mul_f32 v[94:95], v[94:95], v[98:99]
	s_nop 1
	v_mfma_f32_16x16x4_f32 v[4:7], v92, v112, v[4:7]
	v_mfma_f32_16x16x4_f32 v[8:11], v92, v113, v[8:11]
	v_mfma_f32_16x16x4_f32 v[12:15], v92, v114, v[12:15]
	v_mfma_f32_16x16x4_f32 v[16:19], v92, v115, v[16:19]
	v_mfma_f32_16x16x4_f32 v[4:7], v93, v116, v[4:7]
	v_mfma_f32_16x16x4_f32 v[8:11], v93, v117, v[8:11]
	v_mfma_f32_16x16x4_f32 v[12:15], v93, v118, v[12:15]
	v_mfma_f32_16x16x4_f32 v[16:19], v93, v119, v[16:19]
	v_mfma_f32_16x16x4_f32 v[4:7], v94, v120, v[4:7]
	v_mfma_f32_16x16x4_f32 v[8:11], v94, v121, v[8:11]
	v_mfma_f32_16x16x4_f32 v[12:15], v94, v122, v[12:15]
	v_mfma_f32_16x16x4_f32 v[16:19], v94, v123, v[16:19]
	v_mfma_f32_16x16x4_f32 v[4:7], v95, v124, v[4:7]
	v_mfma_f32_16x16x4_f32 v[8:11], v95, v125, v[8:11]
	v_mfma_f32_16x16x4_f32 v[12:15], v95, v126, v[12:15]
	v_mfma_f32_16x16x4_f32 v[16:19], v95, v127, v[16:19]
	v_add_u32_e32 v130, 0x10000, v130
	v_add_u32_e32 v2, 0x10000, v2
	s_nop 0
	global_load_dwordx4 v[92:95], v128, s[66:67] offset:704
	global_load_dwordx4 v[96:99], v129, s[68:69] offset:704
	global_load_dwordx4 v[112:115], v130, s[92:93] offset:-4096
	global_load_dwordx4 v[116:119], v130, s[92:93]
	global_load_dwordx4 v[120:123], v2, s[92:93] offset:-4096
	global_load_dwordx4 v[124:127], v2, s[92:93]
	s_waitcnt vmcnt(12)
	v_pk_mul_f32 v[20:21], v[20:21], v[24:25]
	v_pk_mul_f32 v[22:23], v[22:23], v[26:27]
	s_nop 1
	v_mfma_f32_16x16x4_f32 v[4:7], v20, v28, v[4:7]
	v_mfma_f32_16x16x4_f32 v[8:11], v20, v29, v[8:11]
	v_mfma_f32_16x16x4_f32 v[12:15], v20, v30, v[12:15]
	v_mfma_f32_16x16x4_f32 v[16:19], v20, v31, v[16:19]
	v_mfma_f32_16x16x4_f32 v[4:7], v21, v32, v[4:7]
	v_mfma_f32_16x16x4_f32 v[8:11], v21, v33, v[8:11]
	v_mfma_f32_16x16x4_f32 v[12:15], v21, v34, v[12:15]
	v_mfma_f32_16x16x4_f32 v[16:19], v21, v35, v[16:19]
	v_mfma_f32_16x16x4_f32 v[4:7], v22, v36, v[4:7]
	v_mfma_f32_16x16x4_f32 v[8:11], v22, v37, v[8:11]
	v_mfma_f32_16x16x4_f32 v[12:15], v22, v38, v[12:15]
	v_mfma_f32_16x16x4_f32 v[16:19], v22, v39, v[16:19]
	v_mfma_f32_16x16x4_f32 v[4:7], v23, v40, v[4:7]
	v_mfma_f32_16x16x4_f32 v[8:11], v23, v41, v[8:11]
	v_mfma_f32_16x16x4_f32 v[12:15], v23, v42, v[12:15]
	v_mfma_f32_16x16x4_f32 v[16:19], v23, v43, v[16:19]
	v_add_u32_e32 v130, 0x10000, v130
	v_add_u32_e32 v2, 0x10000, v2
	s_nop 0
	global_load_dwordx4 v[20:23], v128, s[66:67] offset:768
	global_load_dwordx4 v[24:27], v129, s[68:69] offset:768
	global_load_dwordx4 v[28:31], v130, s[92:93] offset:-4096
	global_load_dwordx4 v[32:35], v130, s[92:93]
	global_load_dwordx4 v[36:39], v2, s[92:93] offset:-4096
	global_load_dwordx4 v[40:43], v2, s[92:93]
	s_waitcnt vmcnt(12)
	v_pk_mul_f32 v[44:45], v[44:45], v[48:49]
	v_pk_mul_f32 v[46:47], v[46:47], v[50:51]
	s_nop 1
	v_mfma_f32_16x16x4_f32 v[4:7], v44, v52, v[4:7]
	v_mfma_f32_16x16x4_f32 v[8:11], v44, v53, v[8:11]
	v_mfma_f32_16x16x4_f32 v[12:15], v44, v54, v[12:15]
	v_mfma_f32_16x16x4_f32 v[16:19], v44, v55, v[16:19]
	v_mfma_f32_16x16x4_f32 v[4:7], v45, v56, v[4:7]
	v_mfma_f32_16x16x4_f32 v[8:11], v45, v57, v[8:11]
	v_mfma_f32_16x16x4_f32 v[12:15], v45, v58, v[12:15]
	v_mfma_f32_16x16x4_f32 v[16:19], v45, v59, v[16:19]
	v_mfma_f32_16x16x4_f32 v[4:7], v46, v60, v[4:7]
	v_mfma_f32_16x16x4_f32 v[8:11], v46, v61, v[8:11]
	v_mfma_f32_16x16x4_f32 v[12:15], v46, v62, v[12:15]
	v_mfma_f32_16x16x4_f32 v[16:19], v46, v63, v[16:19]
	v_mfma_f32_16x16x4_f32 v[4:7], v47, v64, v[4:7]
	v_mfma_f32_16x16x4_f32 v[8:11], v47, v65, v[8:11]
	v_mfma_f32_16x16x4_f32 v[12:15], v47, v66, v[12:15]
	v_mfma_f32_16x16x4_f32 v[16:19], v47, v67, v[16:19]
	v_add_u32_e32 v130, 0x10000, v130
	v_add_u32_e32 v2, 0x10000, v2
	s_nop 0
	global_load_dwordx4 v[44:47], v128, s[66:67] offset:832
	global_load_dwordx4 v[48:51], v129, s[68:69] offset:832
	global_load_dwordx4 v[52:55], v130, s[92:93] offset:-4096
	global_load_dwordx4 v[56:59], v130, s[92:93]
	global_load_dwordx4 v[60:63], v2, s[92:93] offset:-4096
	global_load_dwordx4 v[64:67], v2, s[92:93]
	s_waitcnt vmcnt(12)
	v_pk_mul_f32 v[92:93], v[92:93], v[96:97]
	v_pk_mul_f32 v[94:95], v[94:95], v[98:99]
	s_nop 1
	v_mfma_f32_16x16x4_f32 v[4:7], v92, v112, v[4:7]
	v_mfma_f32_16x16x4_f32 v[8:11], v92, v113, v[8:11]
	v_mfma_f32_16x16x4_f32 v[12:15], v92, v114, v[12:15]
	v_mfma_f32_16x16x4_f32 v[16:19], v92, v115, v[16:19]
	v_mfma_f32_16x16x4_f32 v[4:7], v93, v116, v[4:7]
	v_mfma_f32_16x16x4_f32 v[8:11], v93, v117, v[8:11]
	v_mfma_f32_16x16x4_f32 v[12:15], v93, v118, v[12:15]
	v_mfma_f32_16x16x4_f32 v[16:19], v93, v119, v[16:19]
	v_mfma_f32_16x16x4_f32 v[4:7], v94, v120, v[4:7]
	v_mfma_f32_16x16x4_f32 v[8:11], v94, v121, v[8:11]
	v_mfma_f32_16x16x4_f32 v[12:15], v94, v122, v[12:15]
	v_mfma_f32_16x16x4_f32 v[16:19], v94, v123, v[16:19]
	v_mfma_f32_16x16x4_f32 v[4:7], v95, v124, v[4:7]
	v_mfma_f32_16x16x4_f32 v[8:11], v95, v125, v[8:11]
	v_mfma_f32_16x16x4_f32 v[12:15], v95, v126, v[12:15]
	v_mfma_f32_16x16x4_f32 v[16:19], v95, v127, v[16:19]
	v_add_u32_e32 v130, 0x10000, v130
	v_add_u32_e32 v2, 0x10000, v2
	s_nop 0
	global_load_dwordx4 v[92:95], v128, s[66:67] offset:896
	global_load_dwordx4 v[96:99], v129, s[68:69] offset:896
	global_load_dwordx4 v[112:115], v130, s[92:93] offset:-4096
	global_load_dwordx4 v[116:119], v130, s[92:93]
	global_load_dwordx4 v[120:123], v2, s[92:93] offset:-4096
	global_load_dwordx4 v[124:127], v2, s[92:93]
	s_waitcnt vmcnt(12)
	v_pk_mul_f32 v[20:21], v[20:21], v[24:25]
	v_pk_mul_f32 v[22:23], v[22:23], v[26:27]
	s_nop 1
	v_mfma_f32_16x16x4_f32 v[4:7], v20, v28, v[4:7]
	v_mfma_f32_16x16x4_f32 v[8:11], v20, v29, v[8:11]
	v_mfma_f32_16x16x4_f32 v[12:15], v20, v30, v[12:15]
	v_mfma_f32_16x16x4_f32 v[16:19], v20, v31, v[16:19]
	v_mfma_f32_16x16x4_f32 v[4:7], v21, v32, v[4:7]
	v_mfma_f32_16x16x4_f32 v[8:11], v21, v33, v[8:11]
	v_mfma_f32_16x16x4_f32 v[12:15], v21, v34, v[12:15]
	v_mfma_f32_16x16x4_f32 v[16:19], v21, v35, v[16:19]
	v_mfma_f32_16x16x4_f32 v[4:7], v22, v36, v[4:7]
	v_mfma_f32_16x16x4_f32 v[8:11], v22, v37, v[8:11]
	v_mfma_f32_16x16x4_f32 v[12:15], v22, v38, v[12:15]
	v_mfma_f32_16x16x4_f32 v[16:19], v22, v39, v[16:19]
	v_mfma_f32_16x16x4_f32 v[4:7], v23, v40, v[4:7]
	v_mfma_f32_16x16x4_f32 v[8:11], v23, v41, v[8:11]
	v_mfma_f32_16x16x4_f32 v[12:15], v23, v42, v[12:15]
	v_mfma_f32_16x16x4_f32 v[16:19], v23, v43, v[16:19]
	v_add_u32_e32 v130, 0x10000, v130
	v_add_u32_e32 v2, 0x10000, v2
	s_nop 0
	global_load_dwordx4 v[20:23], v128, s[66:67] offset:960
	global_load_dwordx4 v[24:27], v129, s[68:69] offset:960
	global_load_dwordx4 v[28:31], v130, s[92:93] offset:-4096
	global_load_dwordx4 v[32:35], v130, s[92:93]
	global_load_dwordx4 v[36:39], v2, s[92:93] offset:-4096
	global_load_dwordx4 v[40:43], v2, s[92:93]
	s_waitcnt vmcnt(12)
	v_pk_mul_f32 v[44:45], v[44:45], v[48:49]
	v_pk_mul_f32 v[46:47], v[46:47], v[50:51]
	s_nop 1
	v_mfma_f32_16x16x4_f32 v[4:7], v44, v52, v[4:7]
	v_mfma_f32_16x16x4_f32 v[8:11], v44, v53, v[8:11]
	v_mfma_f32_16x16x4_f32 v[12:15], v44, v54, v[12:15]
	v_mfma_f32_16x16x4_f32 v[16:19], v44, v55, v[16:19]
	v_mfma_f32_16x16x4_f32 v[4:7], v45, v56, v[4:7]
	v_mfma_f32_16x16x4_f32 v[8:11], v45, v57, v[8:11]
	v_mfma_f32_16x16x4_f32 v[12:15], v45, v58, v[12:15]
	v_mfma_f32_16x16x4_f32 v[16:19], v45, v59, v[16:19]
	v_mfma_f32_16x16x4_f32 v[4:7], v46, v60, v[4:7]
	v_mfma_f32_16x16x4_f32 v[8:11], v46, v61, v[8:11]
	v_mfma_f32_16x16x4_f32 v[12:15], v46, v62, v[12:15]
	v_mfma_f32_16x16x4_f32 v[16:19], v46, v63, v[16:19]
	v_mfma_f32_16x16x4_f32 v[4:7], v47, v64, v[4:7]
	v_mfma_f32_16x16x4_f32 v[8:11], v47, v65, v[8:11]
	v_mfma_f32_16x16x4_f32 v[12:15], v47, v66, v[12:15]
	v_mfma_f32_16x16x4_f32 v[16:19], v47, v67, v[16:19]
	s_waitcnt vmcnt(6)
	v_pk_mul_f32 v[92:93], v[92:93], v[96:97]
	v_pk_mul_f32 v[94:95], v[94:95], v[98:99]
	s_nop 1
	v_mfma_f32_16x16x4_f32 v[4:7], v92, v112, v[4:7]
	v_mfma_f32_16x16x4_f32 v[8:11], v92, v113, v[8:11]
	v_mfma_f32_16x16x4_f32 v[12:15], v92, v114, v[12:15]
	v_mfma_f32_16x16x4_f32 v[16:19], v92, v115, v[16:19]
	v_mfma_f32_16x16x4_f32 v[4:7], v93, v116, v[4:7]
	v_mfma_f32_16x16x4_f32 v[8:11], v93, v117, v[8:11]
	v_mfma_f32_16x16x4_f32 v[12:15], v93, v118, v[12:15]
	v_mfma_f32_16x16x4_f32 v[16:19], v93, v119, v[16:19]
	v_mfma_f32_16x16x4_f32 v[4:7], v94, v120, v[4:7]
	v_mfma_f32_16x16x4_f32 v[8:11], v94, v121, v[8:11]
	v_mfma_f32_16x16x4_f32 v[12:15], v94, v122, v[12:15]
	v_mfma_f32_16x16x4_f32 v[16:19], v94, v123, v[16:19]
	v_mfma_f32_16x16x4_f32 v[4:7], v95, v124, v[4:7]
	v_mfma_f32_16x16x4_f32 v[8:11], v95, v125, v[8:11]
	v_mfma_f32_16x16x4_f32 v[12:15], v95, v126, v[12:15]
	v_mfma_f32_16x16x4_f32 v[16:19], v95, v127, v[16:19]
	s_waitcnt vmcnt(0)
	v_pk_mul_f32 v[20:21], v[20:21], v[24:25]
	v_pk_mul_f32 v[22:23], v[22:23], v[26:27]
	s_nop 1
	v_mfma_f32_16x16x4_f32 v[4:7], v20, v28, v[4:7]
	v_mfma_f32_16x16x4_f32 v[8:11], v20, v29, v[8:11]
	v_mfma_f32_16x16x4_f32 v[12:15], v20, v30, v[12:15]
	v_mfma_f32_16x16x4_f32 v[16:19], v20, v31, v[16:19]
	v_mfma_f32_16x16x4_f32 v[4:7], v21, v32, v[4:7]
	v_mfma_f32_16x16x4_f32 v[8:11], v21, v33, v[8:11]
	v_mfma_f32_16x16x4_f32 v[12:15], v21, v34, v[12:15]
	v_mfma_f32_16x16x4_f32 v[16:19], v21, v35, v[16:19]
	v_mfma_f32_16x16x4_f32 v[4:7], v22, v36, v[4:7]
	v_mfma_f32_16x16x4_f32 v[8:11], v22, v37, v[8:11]
	v_mfma_f32_16x16x4_f32 v[12:15], v22, v38, v[12:15]
	v_mfma_f32_16x16x4_f32 v[16:19], v22, v39, v[16:19]
	v_mfma_f32_16x16x4_f32 v[4:7], v23, v40, v[4:7]
	v_mfma_f32_16x16x4_f32 v[8:11], v23, v41, v[8:11]
	v_mfma_f32_16x16x4_f32 v[12:15], v23, v42, v[12:15]
	v_mfma_f32_16x16x4_f32 v[16:19], v23, v43, v[16:19]
	s_nop 15
	s_nop 3
	v_cvt_pk_bf16_f32 v20, v4, v5
	v_cvt_pk_bf16_f32 v21, v6, v7
	v_cvt_pk_bf16_f32 v22, v8, v9
	v_cvt_pk_bf16_f32 v23, v10, v11
	v_cvt_pk_bf16_f32 v24, v12, v13
	v_cvt_pk_bf16_f32 v25, v14, v15
	v_cvt_pk_bf16_f32 v26, v16, v17
	v_cvt_pk_bf16_f32 v27, v18, v19
	s_nop 1
	global_store_dwordx2 v131, v[20:21], s[94:95]
	global_store_dwordx2 v131, v[22:23], s[94:95] offset:2048
	global_store_dwordx2 v132, v[24:25], s[94:95]
	global_store_dwordx2 v132, v[26:27], s[94:95] offset:2048
	s_add_i32 s64, s64, s65
	s_waitcnt vmcnt(0)
	s_branch .Lwb_tile
